# v15 with all GEMM epilogue stores plain instead of nontemporal
# baseline (speedup 1.0000x reference)
.LBB0_137:
	v_lshl_add_u32 v159, s48, 10, v154
	ds_read_b32 v160, v159
	v_mov_b32_e32 v162, v116
	v_mov_b32_e32 v163, v124
	v_mov_b32_e32 v164, v112
	v_mov_b32_e32 v165, v120
	s_waitcnt lgkmcnt(0)
	v_pk_mul_f32 v[162:163], v[162:163], v[160:161] op_sel_hi:[1,0]
	v_pk_mul_f32 v[164:165], v[164:165], v[160:161] op_sel_hi:[1,0]
	v_mul_f32_e32 v116, 0xbfb8aa3b, v163
	v_exp_f32_e32 v116, v116
	v_mul_f32_e32 v112, 0xbfb8aa3b, v165
	v_exp_f32_e32 v112, v112
	s_lshl_b32 s0, s30, 7
	v_add_f32_e32 v116, 1.0, v116
	s_and_b32 s0, s0, 0xf80
	v_rcp_f32_e32 v116, v116
	v_or_b32_e32 v128, s0, v155
	s_ashr_i32 s0, s30, 5
	v_add_f32_e32 v112, 1.0, v112
	s_mul_hi_i32 s1, s0, 0x8200000
	s_mul_i32 s0, s0, 0x8200000
	v_rcp_f32_e32 v112, v112
	s_add_u32 s12, s44, s0
	v_lshl_add_u32 v150, s28, 8, v152
	s_addc_u32 s13, s45, s1
	v_lshlrev_b32_e32 v128, 1, v128
	v_mul_f32_e32 v116, v163, v116
	v_mov_b32_e32 v124, v117
	v_lshl_add_u64 v[148:149], s[12:13], 0, v[128:129]
	v_ashrrev_i32_e32 v151, 31, v150
	v_mul_f32_e32 v128, v162, v116
	v_pk_mul_f32 v[116:117], v[124:125], v[160:161] op_sel_hi:[1,0]
	v_lshlrev_b64 v[166:167], 13, v[150:151]
	v_mul_f32_e32 v151, v165, v112
	v_mul_f32_e32 v112, 0xbfb8aa3b, v117
	v_mov_b32_e32 v120, v113
	v_exp_f32_e32 v124, v112
	v_pk_mul_f32 v[112:113], v[120:121], v[160:161] op_sel_hi:[1,0]
	v_mul_f32_e32 v125, v164, v151
	v_mul_f32_e32 v120, 0xbfb8aa3b, v113
	v_exp_f32_e32 v120, v120
	v_add_f32_e32 v121, 1.0, v124
	v_rcp_f32_e32 v124, v121
	v_mov_b32_e32 v121, v126
	v_add_f32_e32 v120, 1.0, v120
	v_rcp_f32_e32 v151, v120
	v_mov_b32_e32 v120, v118
	v_pk_mul_f32 v[120:121], v[120:121], v[160:161] op_sel_hi:[1,0]
	v_mul_f32_e32 v117, v117, v124
	v_mul_f32_e32 v118, 0xbfb8aa3b, v121
	v_exp_f32_e32 v118, v118
	v_mul_f32_e32 v124, v116, v117
	v_mov_b32_e32 v117, v122
	v_mul_f32_e32 v113, v113, v151
	v_add_f32_e32 v116, 1.0, v118
	v_rcp_f32_e32 v118, v116
	v_mov_b32_e32 v116, v114
	v_pk_mul_f32 v[116:117], v[116:117], v[160:161] op_sel_hi:[1,0]
	v_mul_f32_e32 v151, v112, v113
	v_mul_f32_e32 v114, 0xbfb8aa3b, v117
	v_exp_f32_e32 v114, v114
	v_mul_f32_e32 v112, v121, v118
	v_mul_f32_e32 v118, v120, v112
	v_mov_b32_e32 v126, v119
	v_add_f32_e32 v112, 1.0, v114
	v_rcp_f32_e32 v120, v112
	v_pk_mul_f32 v[112:113], v[126:127], v[160:161] op_sel_hi:[1,0]
	v_mov_b32_e32 v122, v115
	v_mul_f32_e32 v114, 0xbfb8aa3b, v113
	v_exp_f32_e32 v119, v114
	v_pk_mul_f32 v[114:115], v[122:123], v[160:161] op_sel_hi:[1,0]
	v_mul_f32_e32 v117, v117, v120
	v_mul_f32_e32 v121, 0xbfb8aa3b, v115
	v_exp_f32_e32 v121, v121
	v_add_f32_e32 v119, 1.0, v119
	v_rcp_f32_e32 v119, v119
	v_mul_f32_e32 v117, v116, v117
	v_add_f32_e32 v120, 1.0, v121
	v_rcp_f32_e32 v120, v120
	v_mul_f32_e32 v113, v113, v119
	v_mul_f32_e32 v116, v112, v113
	v_mov_b32_e32 v121, v104
	v_mul_f32_e32 v112, v115, v120
	v_mul_f32_e32 v119, v114, v112
	v_cvt_pk_bf16_f32 v114, v128, v124
	v_cvt_pk_bf16_f32 v115, v118, v116
	v_cvt_pk_bf16_f32 v116, v125, v151
	v_cvt_pk_bf16_f32 v117, v117, v119
	ds_read_b32 v118, v159 offset:64
	v_lshl_add_u64 v[112:113], v[148:149], 0, v[166:167]
	global_store_dwordx4 v[112:113], v[114:117], off
	v_mov_b32_e32 v120, v96
	v_mov_b32_e32 v104, v97
	v_mov_b32_e32 v116, v100
	v_mov_b32_e32 v117, v108
	s_waitcnt lgkmcnt(0)
	v_pk_mul_f32 v[116:117], v[116:117], v[118:119] op_sel_hi:[1,0]
	v_pk_mul_f32 v[120:121], v[120:121], v[118:119] op_sel_hi:[1,0]
	v_mul_f32_e32 v100, 0xbfb8aa3b, v117
	v_exp_f32_e32 v100, v100
	v_mul_f32_e32 v96, 0xbfb8aa3b, v121
	v_exp_f32_e32 v96, v96
	v_mov_b32_e32 v108, v101
	v_add_f32_e32 v100, 1.0, v100
	v_rcp_f32_e32 v100, v100
	v_add_f32_e32 v96, 1.0, v96
	v_rcp_f32_e32 v96, v96
	v_or_b32_e32 v114, 16, v150
	v_mul_f32_e32 v100, v117, v100
	v_mul_f32_e32 v116, v116, v100
	v_pk_mul_f32 v[100:101], v[108:109], v[118:119] op_sel_hi:[1,0]
	v_mul_f32_e32 v117, v121, v96
	v_mul_f32_e32 v96, 0xbfb8aa3b, v101
	v_exp_f32_e32 v108, v96
	v_pk_mul_f32 v[96:97], v[104:105], v[118:119] op_sel_hi:[1,0]
	v_mul_f32_e32 v109, v120, v117
	v_mul_f32_e32 v104, 0xbfb8aa3b, v97
	v_exp_f32_e32 v104, v104
	v_add_f32_e32 v105, 1.0, v108
	v_rcp_f32_e32 v108, v105
	v_mov_b32_e32 v105, v110
	v_add_f32_e32 v104, 1.0, v104
	v_rcp_f32_e32 v117, v104
	v_mov_b32_e32 v104, v102
	v_pk_mul_f32 v[104:105], v[104:105], v[118:119] op_sel_hi:[1,0]
	v_mul_f32_e32 v101, v101, v108
	v_mul_f32_e32 v102, 0xbfb8aa3b, v105
	v_exp_f32_e32 v102, v102
	v_mul_f32_e32 v108, v100, v101
	v_mov_b32_e32 v101, v106
	v_mul_f32_e32 v97, v97, v117
	v_add_f32_e32 v100, 1.0, v102
	v_rcp_f32_e32 v102, v100
	v_mov_b32_e32 v100, v98
	v_pk_mul_f32 v[100:101], v[100:101], v[118:119] op_sel_hi:[1,0]
	v_mul_f32_e32 v117, v96, v97
	v_mul_f32_e32 v98, 0xbfb8aa3b, v101
	v_exp_f32_e32 v98, v98
	v_mul_f32_e32 v96, v105, v102
	v_mul_f32_e32 v102, v104, v96
	v_mov_b32_e32 v110, v103
	v_add_f32_e32 v96, 1.0, v98
	v_rcp_f32_e32 v104, v96
	v_pk_mul_f32 v[96:97], v[110:111], v[118:119] op_sel_hi:[1,0]
	v_mov_b32_e32 v106, v99
	v_mul_f32_e32 v98, 0xbfb8aa3b, v97
	v_exp_f32_e32 v103, v98
	v_pk_mul_f32 v[98:99], v[106:107], v[118:119] op_sel_hi:[1,0]
	v_mul_f32_e32 v101, v101, v104
	v_mul_f32_e32 v105, 0xbfb8aa3b, v99
	v_exp_f32_e32 v105, v105
	v_add_f32_e32 v103, 1.0, v103
	v_rcp_f32_e32 v103, v103
	v_mul_f32_e32 v100, v100, v101
	v_add_f32_e32 v104, 1.0, v105
	v_rcp_f32_e32 v104, v104
	v_mul_f32_e32 v97, v97, v103
	v_mul_f32_e32 v97, v96, v97
	v_ashrrev_i32_e32 v115, 31, v114
	v_mul_f32_e32 v96, v99, v104
	v_mul_f32_e32 v99, v98, v96
	v_cvt_pk_bf16_f32 v96, v116, v108
	v_cvt_pk_bf16_f32 v97, v102, v97
	v_cvt_pk_bf16_f32 v98, v109, v117
	v_cvt_pk_bf16_f32 v99, v100, v99
	ds_read_b32 v100, v159 offset:128
	v_lshlrev_b64 v[114:115], 13, v[114:115]
	v_lshl_add_u64 v[102:103], v[148:149], 0, v[114:115]
	global_store_dwordx4 v[102:103], v[96:99], off
	v_or_b32_e32 v102, 32, v150
	v_ashrrev_i32_e32 v103, 31, v102
	v_mov_b32_e32 v96, v84
	v_mov_b32_e32 v97, v92
	s_waitcnt lgkmcnt(0)
	v_pk_mul_f32 v[96:97], v[96:97], v[100:101] op_sel_hi:[1,0]
	v_mov_b32_e32 v98, v80
	v_mul_f32_e32 v84, 0xbfb8aa3b, v97
	v_mov_b32_e32 v99, v88
	v_exp_f32_e32 v84, v84
	v_pk_mul_f32 v[98:99], v[98:99], v[100:101] op_sel_hi:[1,0]
	v_mov_b32_e32 v92, v85
	v_mul_f32_e32 v80, 0xbfb8aa3b, v99
	v_exp_f32_e32 v80, v80
	v_add_f32_e32 v84, 1.0, v84
	v_rcp_f32_e32 v84, v84
	v_mov_b32_e32 v88, v81
	v_add_f32_e32 v80, 1.0, v80
	v_rcp_f32_e32 v80, v80
	v_mul_f32_e32 v84, v97, v84
	v_mul_f32_e32 v96, v96, v84
	v_pk_mul_f32 v[84:85], v[92:93], v[100:101] op_sel_hi:[1,0]
	v_mul_f32_e32 v97, v99, v80
	v_mul_f32_e32 v80, 0xbfb8aa3b, v85
	v_exp_f32_e32 v92, v80
	v_pk_mul_f32 v[80:81], v[88:89], v[100:101] op_sel_hi:[1,0]
	v_mul_f32_e32 v93, v98, v97
	v_mul_f32_e32 v88, 0xbfb8aa3b, v81
	v_exp_f32_e32 v88, v88
	v_add_f32_e32 v89, 1.0, v92
	v_rcp_f32_e32 v92, v89
	v_mov_b32_e32 v89, v94
	v_add_f32_e32 v88, 1.0, v88
	v_rcp_f32_e32 v97, v88
	v_mov_b32_e32 v88, v86
	v_pk_mul_f32 v[88:89], v[88:89], v[100:101] op_sel_hi:[1,0]
	v_mul_f32_e32 v85, v85, v92
	v_mul_f32_e32 v86, 0xbfb8aa3b, v89
	v_exp_f32_e32 v86, v86
	v_mul_f32_e32 v92, v84, v85
	v_mov_b32_e32 v85, v90
	v_mul_f32_e32 v81, v81, v97
	v_add_f32_e32 v84, 1.0, v86
	v_rcp_f32_e32 v86, v84
	v_mov_b32_e32 v84, v82
	v_pk_mul_f32 v[84:85], v[84:85], v[100:101] op_sel_hi:[1,0]
	v_mul_f32_e32 v97, v80, v81
	v_mul_f32_e32 v82, 0xbfb8aa3b, v85
	v_exp_f32_e32 v82, v82
	v_mul_f32_e32 v80, v89, v86
	v_mul_f32_e32 v86, v88, v80
	v_mov_b32_e32 v94, v87
	v_add_f32_e32 v80, 1.0, v82
	v_rcp_f32_e32 v88, v80
	v_pk_mul_f32 v[80:81], v[94:95], v[100:101] op_sel_hi:[1,0]
	v_mov_b32_e32 v90, v83
	v_mul_f32_e32 v82, 0xbfb8aa3b, v81
	v_exp_f32_e32 v87, v82
	v_pk_mul_f32 v[82:83], v[90:91], v[100:101] op_sel_hi:[1,0]
	v_mul_f32_e32 v85, v85, v88
	v_mul_f32_e32 v89, 0xbfb8aa3b, v83
	v_exp_f32_e32 v89, v89
	v_add_f32_e32 v87, 1.0, v87
	v_rcp_f32_e32 v87, v87
	v_mul_f32_e32 v84, v84, v85
	v_add_f32_e32 v88, 1.0, v89
	v_rcp_f32_e32 v88, v88
	v_mul_f32_e32 v81, v81, v87
	v_mul_f32_e32 v81, v80, v81
	v_mov_b32_e32 v89, v76
	v_mul_f32_e32 v80, v83, v88
	v_mul_f32_e32 v83, v82, v80
	v_cvt_pk_bf16_f32 v80, v96, v92
	v_cvt_pk_bf16_f32 v81, v86, v81
	v_cvt_pk_bf16_f32 v82, v93, v97
	v_cvt_pk_bf16_f32 v83, v84, v83
	ds_read_b32 v84, v159 offset:192
	v_mov_b32_e32 v88, v68
	v_mov_b32_e32 v90, v64
	v_mov_b32_e32 v91, v72
	v_lshlrev_b64 v[86:87], 13, v[102:103]
	s_waitcnt lgkmcnt(0)
	v_pk_mul_f32 v[88:89], v[88:89], v[84:85] op_sel_hi:[1,0]
	v_pk_mul_f32 v[90:91], v[90:91], v[84:85] op_sel_hi:[1,0]
	v_mul_f32_e32 v68, 0xbfb8aa3b, v89
	v_exp_f32_e32 v68, v68
	v_mul_f32_e32 v64, 0xbfb8aa3b, v91
	v_exp_f32_e32 v64, v64
	v_mov_b32_e32 v76, v69
	v_add_f32_e32 v68, 1.0, v68
	v_rcp_f32_e32 v72, v68
	v_add_f32_e32 v64, 1.0, v64
	v_rcp_f32_e32 v64, v64
	v_lshl_add_u64 v[86:87], v[148:149], 0, v[86:87]
	v_mul_f32_e32 v72, v89, v72
	v_pk_mul_f32 v[76:77], v[76:77], v[84:85] op_sel_hi:[1,0]
	global_store_dwordx4 v[86:87], v[80:83], off
	v_or_b32_e32 v68, 48, v150
	s_nop 0
	v_mul_f32_e32 v80, v88, v72
	v_mul_f32_e32 v81, v91, v64
	v_mul_f32_e32 v64, 0xbfb8aa3b, v77
	v_mov_b32_e32 v72, v65
	v_exp_f32_e32 v69, v64
	v_pk_mul_f32 v[64:65], v[72:73], v[84:85] op_sel_hi:[1,0]
	v_mov_b32_e32 v73, v78
	v_mul_f32_e32 v72, 0xbfb8aa3b, v65
	v_exp_f32_e32 v72, v72
	v_add_f32_e32 v69, 1.0, v69
	v_rcp_f32_e32 v69, v69
	v_mov_b32_e32 v78, v71
	v_add_f32_e32 v72, 1.0, v72
	v_rcp_f32_e32 v82, v72
	v_mov_b32_e32 v72, v70
	v_pk_mul_f32 v[72:73], v[72:73], v[84:85] op_sel_hi:[1,0]
	v_mul_f32_e32 v69, v77, v69
	v_mul_f32_e32 v70, 0xbfb8aa3b, v73
	v_exp_f32_e32 v70, v70
	v_mul_f32_e32 v69, v76, v69
	v_mov_b32_e32 v76, v66
	v_mov_b32_e32 v77, v74
	v_add_f32_e32 v70, 1.0, v70
	v_pk_mul_f32 v[76:77], v[76:77], v[84:85] op_sel_hi:[1,0]
	v_rcp_f32_e32 v70, v70
	v_mul_f32_e32 v66, 0xbfb8aa3b, v77
	v_exp_f32_e32 v66, v66
	v_mul_f32_e32 v65, v65, v82
	v_mul_f32_e32 v82, v64, v65
	v_mul_f32_e32 v64, v73, v70
	v_mul_f32_e32 v70, v72, v64
	v_add_f32_e32 v64, 1.0, v66
	v_rcp_f32_e32 v72, v64
	v_pk_mul_f32 v[64:65], v[78:79], v[84:85] op_sel_hi:[1,0]
	v_mov_b32_e32 v74, v67
	v_mul_f32_e32 v66, 0xbfb8aa3b, v65
	v_exp_f32_e32 v71, v66
	v_pk_mul_f32 v[66:67], v[74:75], v[84:85] op_sel_hi:[1,0]
	v_mul_f32_e32 v72, v77, v72
	v_mul_f32_e32 v73, 0xbfb8aa3b, v67
	v_exp_f32_e32 v73, v73
	v_add_f32_e32 v71, 1.0, v71
	v_rcp_f32_e32 v71, v71
	v_mul_f32_e32 v81, v90, v81
	v_add_f32_e32 v73, 1.0, v73
	v_rcp_f32_e32 v73, v73
	v_mul_f32_e32 v65, v65, v71
	v_mul_f32_e32 v65, v64, v65
	v_mul_f32_e32 v72, v76, v72
	v_mul_f32_e32 v64, v67, v73
	v_mul_f32_e32 v67, v66, v64
	v_cvt_pk_bf16_f32 v64, v80, v69
	v_cvt_pk_bf16_f32 v65, v70, v65
	v_cvt_pk_bf16_f32 v66, v81, v82
	v_cvt_pk_bf16_f32 v67, v72, v67
	ds_read_b32 v70, v159 offset:512
	v_mov_b32_e32 v72, v52
	v_mov_b32_e32 v73, v60
	v_mov_b32_e32 v74, v48
	v_mov_b32_e32 v75, v56
	s_waitcnt lgkmcnt(0)
	v_pk_mul_f32 v[72:73], v[72:73], v[70:71] op_sel_hi:[1,0]
	v_pk_mul_f32 v[74:75], v[74:75], v[70:71] op_sel_hi:[1,0]
	v_mul_f32_e32 v52, 0xbfb8aa3b, v73
	v_exp_f32_e32 v52, v52
	v_mul_f32_e32 v48, 0xbfb8aa3b, v75
	v_exp_f32_e32 v48, v48
	v_ashrrev_i32_e32 v69, 31, v68
	v_add_f32_e32 v52, 1.0, v52
	v_rcp_f32_e32 v52, v52
	v_add_f32_e32 v48, 1.0, v48
	v_rcp_f32_e32 v48, v48
	v_lshlrev_b64 v[68:69], 13, v[68:69]
	v_lshl_add_u64 v[68:69], v[148:149], 0, v[68:69]
	v_mul_f32_e32 v52, v73, v52
	v_mov_b32_e32 v60, v53
	global_store_dwordx4 v[68:69], v[64:67], off
	v_mov_b32_e32 v56, v49
	s_nop 0
	v_mul_f32_e32 v64, v72, v52
	v_pk_mul_f32 v[52:53], v[60:61], v[70:71] op_sel_hi:[1,0]
	v_mul_f32_e32 v65, v75, v48
	v_mul_f32_e32 v48, 0xbfb8aa3b, v53
	v_exp_f32_e32 v60, v48
	v_pk_mul_f32 v[48:49], v[56:57], v[70:71] op_sel_hi:[1,0]
	v_mul_f32_e32 v61, v74, v65
	v_mul_f32_e32 v56, 0xbfb8aa3b, v49
	v_exp_f32_e32 v56, v56
	v_add_f32_e32 v57, 1.0, v60
	v_rcp_f32_e32 v60, v57
	v_mov_b32_e32 v57, v62
	v_add_f32_e32 v56, 1.0, v56
	v_rcp_f32_e32 v65, v56
	v_mov_b32_e32 v56, v54
	v_pk_mul_f32 v[56:57], v[56:57], v[70:71] op_sel_hi:[1,0]
	v_mul_f32_e32 v53, v53, v60
	v_mul_f32_e32 v54, 0xbfb8aa3b, v57
	v_exp_f32_e32 v54, v54
	v_mul_f32_e32 v60, v52, v53
	v_mov_b32_e32 v53, v58
	v_mul_f32_e32 v49, v49, v65
	v_add_f32_e32 v52, 1.0, v54
	v_rcp_f32_e32 v54, v52
	v_mov_b32_e32 v52, v50
	v_pk_mul_f32 v[52:53], v[52:53], v[70:71] op_sel_hi:[1,0]
	v_mul_f32_e32 v65, v48, v49
	v_mul_f32_e32 v50, 0xbfb8aa3b, v53
	v_exp_f32_e32 v50, v50
	v_mul_f32_e32 v48, v57, v54
	v_mul_f32_e32 v54, v56, v48
	v_mov_b32_e32 v62, v55
	v_add_f32_e32 v48, 1.0, v50
	v_rcp_f32_e32 v56, v48
	v_pk_mul_f32 v[48:49], v[62:63], v[70:71] op_sel_hi:[1,0]
	v_mov_b32_e32 v58, v51
	v_mul_f32_e32 v50, 0xbfb8aa3b, v49
	v_exp_f32_e32 v55, v50
	v_pk_mul_f32 v[50:51], v[58:59], v[70:71] op_sel_hi:[1,0]
	v_mul_f32_e32 v53, v53, v56
	v_mul_f32_e32 v57, 0xbfb8aa3b, v51
	v_exp_f32_e32 v57, v57
	v_add_f32_e32 v55, 1.0, v55
	v_rcp_f32_e32 v55, v55
	v_mul_f32_e32 v52, v52, v53
	v_add_f32_e32 v56, 1.0, v57
	v_rcp_f32_e32 v56, v56
	v_mul_f32_e32 v49, v49, v55
	v_mul_f32_e32 v49, v48, v49
	v_mov_b32_e32 v55, v44
	v_mul_f32_e32 v48, v51, v56
	v_mul_f32_e32 v51, v50, v48
	v_cvt_pk_bf16_f32 v48, v64, v60
	v_cvt_pk_bf16_f32 v49, v54, v49
	v_cvt_pk_bf16_f32 v50, v61, v65
	v_cvt_pk_bf16_f32 v51, v52, v51
	ds_read_b32 v52, v159 offset:576
	v_mov_b32_e32 v54, v36
	v_mov_b32_e32 v56, v32
	v_mov_b32_e32 v57, v40
	v_add_co_u32_e32 v58, vcc, s53, v112
	s_waitcnt lgkmcnt(0)
	v_pk_mul_f32 v[54:55], v[54:55], v[52:53] op_sel_hi:[1,0]
	v_pk_mul_f32 v[56:57], v[56:57], v[52:53] op_sel_hi:[1,0]
	v_mul_f32_e32 v36, 0xbfb8aa3b, v55
	v_exp_f32_e32 v36, v36
	v_mul_f32_e32 v32, 0xbfb8aa3b, v57
	v_exp_f32_e32 v32, v32
	v_addc_co_u32_e32 v59, vcc, 0, v113, vcc
	v_add_f32_e32 v36, 1.0, v36
	v_rcp_f32_e32 v36, v36
	v_add_f32_e32 v32, 1.0, v32
	v_rcp_f32_e32 v32, v32
	v_mov_b32_e32 v44, v37
	v_mul_f32_e32 v36, v55, v36
	global_store_dwordx4 v[58:59], v[48:51], off
	v_mov_b32_e32 v40, v33
	s_nop 0
	v_mul_f32_e32 v48, v54, v36
	v_pk_mul_f32 v[36:37], v[44:45], v[52:53] op_sel_hi:[1,0]
	v_mul_f32_e32 v49, v57, v32
	v_mul_f32_e32 v32, 0xbfb8aa3b, v37
	v_exp_f32_e32 v44, v32
	v_pk_mul_f32 v[32:33], v[40:41], v[52:53] op_sel_hi:[1,0]
	v_mul_f32_e32 v45, v56, v49
	v_mul_f32_e32 v40, 0xbfb8aa3b, v33
	v_exp_f32_e32 v40, v40
	v_add_f32_e32 v41, 1.0, v44
	v_rcp_f32_e32 v44, v41
	v_mov_b32_e32 v41, v46
	v_add_f32_e32 v40, 1.0, v40
	v_rcp_f32_e32 v49, v40
	v_mov_b32_e32 v40, v38
	v_pk_mul_f32 v[40:41], v[40:41], v[52:53] op_sel_hi:[1,0]
	v_mul_f32_e32 v37, v37, v44
	v_mul_f32_e32 v38, 0xbfb8aa3b, v41
	v_exp_f32_e32 v38, v38
	v_mul_f32_e32 v44, v36, v37
	v_mov_b32_e32 v37, v42
	v_mul_f32_e32 v33, v33, v49
	v_add_f32_e32 v36, 1.0, v38
	v_rcp_f32_e32 v38, v36
	v_mov_b32_e32 v36, v34
	v_pk_mul_f32 v[36:37], v[36:37], v[52:53] op_sel_hi:[1,0]
	v_mul_f32_e32 v49, v32, v33
	v_mul_f32_e32 v34, 0xbfb8aa3b, v37
	v_exp_f32_e32 v34, v34
	v_mul_f32_e32 v32, v41, v38
	v_mul_f32_e32 v38, v40, v32
	v_mov_b32_e32 v46, v39
	v_add_f32_e32 v32, 1.0, v34
	v_rcp_f32_e32 v40, v32
	v_pk_mul_f32 v[32:33], v[46:47], v[52:53] op_sel_hi:[1,0]
	v_mov_b32_e32 v42, v35
	v_mul_f32_e32 v34, 0xbfb8aa3b, v33
	v_exp_f32_e32 v39, v34
	v_pk_mul_f32 v[34:35], v[42:43], v[52:53] op_sel_hi:[1,0]
	v_mul_f32_e32 v37, v37, v40
	v_mul_f32_e32 v41, 0xbfb8aa3b, v35
	v_exp_f32_e32 v41, v41
	v_add_f32_e32 v39, 1.0, v39
	v_rcp_f32_e32 v39, v39
	v_mul_f32_e32 v36, v36, v37
	v_add_f32_e32 v40, 1.0, v41
	v_rcp_f32_e32 v40, v40
	v_mul_f32_e32 v33, v33, v39
	v_mul_f32_e32 v33, v32, v33
	v_mov_b32_e32 v39, v28
	v_mul_f32_e32 v32, v35, v40
	v_mul_f32_e32 v35, v34, v32
	v_cvt_pk_bf16_f32 v32, v48, v44
	v_cvt_pk_bf16_f32 v33, v38, v33
	v_cvt_pk_bf16_f32 v34, v45, v49
	v_cvt_pk_bf16_f32 v35, v36, v35
	ds_read_b32 v36, v159 offset:640
	v_mov_b32_e32 v38, v20
	v_mov_b32_e32 v40, v16
	v_mov_b32_e32 v41, v24
	v_add_co_u32_e32 v42, vcc, s54, v112
	s_waitcnt lgkmcnt(0)
	v_pk_mul_f32 v[38:39], v[38:39], v[36:37] op_sel_hi:[1,0]
	v_pk_mul_f32 v[40:41], v[40:41], v[36:37] op_sel_hi:[1,0]
	v_mul_f32_e32 v20, 0xbfb8aa3b, v39
	v_exp_f32_e32 v20, v20
	v_mul_f32_e32 v16, 0xbfb8aa3b, v41
	v_exp_f32_e32 v16, v16
	v_addc_co_u32_e32 v43, vcc, 0, v113, vcc
	v_add_f32_e32 v20, 1.0, v20
	v_rcp_f32_e32 v20, v20
	v_add_f32_e32 v16, 1.0, v16
	v_rcp_f32_e32 v16, v16
	v_mov_b32_e32 v28, v21
	v_mul_f32_e32 v20, v39, v20
	global_store_dwordx4 v[42:43], v[32:35], off
	v_mov_b32_e32 v24, v17
	s_nop 0
	v_mul_f32_e32 v32, v38, v20
	v_pk_mul_f32 v[20:21], v[28:29], v[36:37] op_sel_hi:[1,0]
	v_mul_f32_e32 v33, v41, v16
	v_mul_f32_e32 v16, 0xbfb8aa3b, v21
	v_exp_f32_e32 v28, v16
	v_pk_mul_f32 v[16:17], v[24:25], v[36:37] op_sel_hi:[1,0]
	v_mul_f32_e32 v29, v40, v33
	v_mul_f32_e32 v24, 0xbfb8aa3b, v17
	v_exp_f32_e32 v24, v24
	v_add_f32_e32 v25, 1.0, v28
	v_rcp_f32_e32 v28, v25
	v_mov_b32_e32 v25, v30
	v_add_f32_e32 v24, 1.0, v24
	v_rcp_f32_e32 v33, v24
	v_mov_b32_e32 v24, v22
	v_pk_mul_f32 v[24:25], v[24:25], v[36:37] op_sel_hi:[1,0]
	v_mul_f32_e32 v21, v21, v28
	v_mul_f32_e32 v22, 0xbfb8aa3b, v25
	v_exp_f32_e32 v22, v22
	v_mul_f32_e32 v28, v20, v21
	v_mov_b32_e32 v21, v26
	v_mul_f32_e32 v17, v17, v33
	v_add_f32_e32 v20, 1.0, v22
	v_rcp_f32_e32 v22, v20
	v_mov_b32_e32 v20, v18
	v_pk_mul_f32 v[20:21], v[20:21], v[36:37] op_sel_hi:[1,0]
	v_mul_f32_e32 v33, v16, v17
	v_mul_f32_e32 v18, 0xbfb8aa3b, v21
	v_exp_f32_e32 v18, v18
	v_mul_f32_e32 v16, v25, v22
	v_mul_f32_e32 v22, v24, v16
	v_mov_b32_e32 v30, v23
	v_add_f32_e32 v16, 1.0, v18
	v_rcp_f32_e32 v24, v16
	v_pk_mul_f32 v[16:17], v[30:31], v[36:37] op_sel_hi:[1,0]
	v_mov_b32_e32 v26, v19
	v_mul_f32_e32 v18, 0xbfb8aa3b, v17
	v_exp_f32_e32 v23, v18
	v_pk_mul_f32 v[18:19], v[26:27], v[36:37] op_sel_hi:[1,0]
	v_mul_f32_e32 v21, v21, v24
	v_mul_f32_e32 v25, 0xbfb8aa3b, v19
	v_exp_f32_e32 v25, v25
	v_add_f32_e32 v23, 1.0, v23
	v_rcp_f32_e32 v23, v23
	v_mul_f32_e32 v20, v20, v21
	v_add_f32_e32 v24, 1.0, v25
	v_rcp_f32_e32 v24, v24
	v_mul_f32_e32 v17, v17, v23
	v_mul_f32_e32 v17, v16, v17
	v_mov_b32_e32 v23, v12
	v_mul_f32_e32 v16, v19, v24
	v_mul_f32_e32 v19, v18, v16
	v_cvt_pk_bf16_f32 v16, v32, v28
	v_cvt_pk_bf16_f32 v17, v22, v17
	v_cvt_pk_bf16_f32 v18, v29, v33
	v_cvt_pk_bf16_f32 v19, v20, v19
	ds_read_b32 v20, v159 offset:704
	v_mov_b32_e32 v22, v4
	v_mov_b32_e32 v24, v0
	v_mov_b32_e32 v25, v8
	v_add_co_u32_e32 v26, vcc, s55, v112
	s_waitcnt lgkmcnt(0)
	v_pk_mul_f32 v[22:23], v[22:23], v[20:21] op_sel_hi:[1,0]
	v_pk_mul_f32 v[24:25], v[24:25], v[20:21] op_sel_hi:[1,0]
	v_mul_f32_e32 v4, 0xbfb8aa3b, v23
	v_exp_f32_e32 v4, v4
	v_mul_f32_e32 v0, 0xbfb8aa3b, v25
	v_exp_f32_e32 v0, v0
	v_addc_co_u32_e32 v27, vcc, 0, v113, vcc
	v_add_f32_e32 v4, 1.0, v4
	v_rcp_f32_e32 v4, v4
	v_add_f32_e32 v0, 1.0, v0
	v_rcp_f32_e32 v0, v0
	v_mov_b32_e32 v12, v5
	v_mul_f32_e32 v4, v23, v4
	global_store_dwordx4 v[26:27], v[16:19], off
	v_mov_b32_e32 v8, v1
	s_nop 0
	v_mul_f32_e32 v16, v22, v4
	v_pk_mul_f32 v[4:5], v[12:13], v[20:21] op_sel_hi:[1,0]
	v_mul_f32_e32 v17, v25, v0
	v_mul_f32_e32 v0, 0xbfb8aa3b, v5
	v_exp_f32_e32 v12, v0
	v_pk_mul_f32 v[0:1], v[8:9], v[20:21] op_sel_hi:[1,0]
	v_mul_f32_e32 v13, v24, v17
	v_mul_f32_e32 v8, 0xbfb8aa3b, v1
	v_exp_f32_e32 v8, v8
	v_add_f32_e32 v9, 1.0, v12
	v_rcp_f32_e32 v12, v9
	v_mov_b32_e32 v9, v14
	v_add_f32_e32 v8, 1.0, v8
	v_rcp_f32_e32 v17, v8
	v_mov_b32_e32 v8, v6
	v_pk_mul_f32 v[8:9], v[8:9], v[20:21] op_sel_hi:[1,0]
	v_mul_f32_e32 v5, v5, v12
	v_mul_f32_e32 v6, 0xbfb8aa3b, v9
	v_exp_f32_e32 v6, v6
	v_mul_f32_e32 v12, v4, v5
	v_mov_b32_e32 v5, v10
	v_mul_f32_e32 v1, v1, v17
	v_add_f32_e32 v4, 1.0, v6
	v_rcp_f32_e32 v6, v4
	v_mov_b32_e32 v4, v2
	v_pk_mul_f32 v[4:5], v[4:5], v[20:21] op_sel_hi:[1,0]
	v_mul_f32_e32 v17, v0, v1
	v_mul_f32_e32 v2, 0xbfb8aa3b, v5
	v_exp_f32_e32 v2, v2
	v_mul_f32_e32 v0, v9, v6
	v_mul_f32_e32 v6, v8, v0
	v_mov_b32_e32 v14, v7
	v_add_f32_e32 v0, 1.0, v2
	v_rcp_f32_e32 v8, v0
	v_pk_mul_f32 v[0:1], v[14:15], v[20:21] op_sel_hi:[1,0]
	v_mov_b32_e32 v10, v3
	v_mul_f32_e32 v2, 0xbfb8aa3b, v1
	v_exp_f32_e32 v7, v2
	v_pk_mul_f32 v[2:3], v[10:11], v[20:21] op_sel_hi:[1,0]
	v_mul_f32_e32 v5, v5, v8
	v_mul_f32_e32 v9, 0xbfb8aa3b, v3
	v_exp_f32_e32 v9, v9
	v_add_f32_e32 v7, 1.0, v7
	v_rcp_f32_e32 v7, v7
	v_mul_f32_e32 v4, v4, v5
	v_add_f32_e32 v8, 1.0, v9
	v_rcp_f32_e32 v8, v8
	v_mul_f32_e32 v1, v1, v7
	v_mul_f32_e32 v1, v0, v1
	v_mul_f32_e32 v0, v3, v8
	v_mul_f32_e32 v3, v2, v0
	v_cvt_pk_bf16_f32 v0, v16, v12
	v_cvt_pk_bf16_f32 v1, v6, v1
	v_cvt_pk_bf16_f32 v2, v13, v17
	v_cvt_pk_bf16_f32 v3, v4, v3
	v_add_co_u32_e32 v4, vcc, 0x160000, v112
	s_nop 1
	v_addc_co_u32_e32 v5, vcc, 0, v113, vcc
	s_andn2_b64 vcc, exec, s[2:3]
	s_mov_b64 s[2:3], -1
	global_store_dwordx4 v[4:5], v[0:3], off
	s_cbranch_vccnz .LBB0_130
	s_andn2_b64 vcc, exec, s[4:5]
	s_xor_b32 s48, s48, 1
	s_cbranch_vccnz .LBB0_140
	s_lshl_b32 s0, s48, 10
	s_add_i32 s0, s0, 0
	s_lshl_b64 s[2:3], s[16:17], 10
	s_add_i32 m0, s0, 0x20000
	v_lshl_add_u64 v[0:1], v[138:139], 0, s[2:3]
	global_load_lds_dwordx4 v[0:1], off

.LBB0_434:
	v_lshl_add_u32 v146, s42, 8, v142
	v_lshl_or_b32 v140, s12, 8, v144
	v_ashrrev_i32_e32 v147, 31, v146
	v_ashrrev_i32_e32 v141, 31, v140
	v_lshlrev_b64 v[148:149], 13, v[146:147]
	v_lshl_add_u64 v[148:149], s[10:11], 0, v[148:149]
	v_lshlrev_b64 v[150:151], 1, v[140:141]
	v_lshl_add_u64 v[140:141], v[148:149], 0, v[150:151]
	v_cvt_pk_bf16_f32 v124, v124, v125
	v_cvt_pk_bf16_f32 v125, v126, v127
	v_cvt_pk_bf16_f32 v126, v120, v121
	v_cvt_pk_bf16_f32 v127, v122, v123
	global_store_dwordx4 v[140:141], v[124:127], off
	v_cvt_pk_bf16_f32 v112, v112, v113
	v_cvt_pk_bf16_f32 v113, v114, v115
	v_cvt_pk_bf16_f32 v114, v104, v105
	v_or_b32_e32 v104, 16, v146
	v_ashrrev_i32_e32 v105, 31, v104
	v_lshlrev_b64 v[104:105], 13, v[104:105]
	v_lshl_add_u64 v[104:105], s[10:11], 0, v[104:105]
	v_cvt_pk_bf16_f32 v115, v106, v107
	global_store_dwordx4 v[140:141], v[112:115], off offset:256
	s_nop 1
	v_lshl_add_u64 v[112:113], v[104:105], 0, v[150:151]
	v_cvt_pk_bf16_f32 v104, v116, v117
	v_cvt_pk_bf16_f32 v105, v118, v119
	v_cvt_pk_bf16_f32 v106, v108, v109
	v_cvt_pk_bf16_f32 v107, v110, v111
	global_store_dwordx4 v[112:113], v[104:107], off
	v_cvt_pk_bf16_f32 v96, v96, v97
	v_cvt_pk_bf16_f32 v97, v98, v99
	v_cvt_pk_bf16_f32 v98, v88, v89
	v_or_b32_e32 v88, 32, v146
	v_ashrrev_i32_e32 v89, 31, v88
	v_lshlrev_b64 v[88:89], 13, v[88:89]
	v_lshl_add_u64 v[88:89], s[10:11], 0, v[88:89]
	v_cvt_pk_bf16_f32 v99, v90, v91
	global_store_dwordx4 v[112:113], v[96:99], off offset:256
	s_nop 1
	v_lshl_add_u64 v[96:97], v[88:89], 0, v[150:151]
	v_cvt_pk_bf16_f32 v88, v100, v101
	v_cvt_pk_bf16_f32 v89, v102, v103
	v_cvt_pk_bf16_f32 v90, v92, v93
	v_cvt_pk_bf16_f32 v91, v94, v95
	global_store_dwordx4 v[96:97], v[88:91], off
	v_cvt_pk_bf16_f32 v80, v80, v81
	v_cvt_pk_bf16_f32 v81, v82, v83
	v_cvt_pk_bf16_f32 v82, v72, v73
	v_or_b32_e32 v72, 48, v146
	v_ashrrev_i32_e32 v73, 31, v72
	v_lshlrev_b64 v[72:73], 13, v[72:73]
	v_lshl_add_u64 v[72:73], s[10:11], 0, v[72:73]
	v_cvt_pk_bf16_f32 v83, v74, v75
	global_store_dwordx4 v[96:97], v[80:83], off offset:256
	s_nop 1
	v_lshl_add_u64 v[80:81], v[72:73], 0, v[150:151]
	v_cvt_pk_bf16_f32 v72, v84, v85
	v_cvt_pk_bf16_f32 v73, v86, v87
	v_cvt_pk_bf16_f32 v74, v76, v77
	v_cvt_pk_bf16_f32 v75, v78, v79
	global_store_dwordx4 v[80:81], v[72:75], off
	v_cvt_pk_bf16_f32 v68, v68, v69
	v_cvt_pk_bf16_f32 v69, v70, v71
	v_cvt_pk_bf16_f32 v70, v64, v65
	v_cvt_pk_bf16_f32 v71, v66, v67
	global_store_dwordx4 v[80:81], v[68:71], off offset:256
	v_cvt_pk_bf16_f32 v60, v60, v61
	v_cvt_pk_bf16_f32 v61, v62, v63
	v_cvt_pk_bf16_f32 v62, v56, v57
	v_add_co_u32_e32 v56, vcc, s69, v140
	v_lshl_add_u64 v[64:65], v[140:141], 0, s[6:7]
	s_nop 0
	v_addc_co_u32_e32 v57, vcc, 0, v141, vcc
	v_cvt_pk_bf16_f32 v63, v58, v59
	global_store_dwordx4 v[56:57], v[60:63], off
	v_cvt_pk_bf16_f32 v48, v48, v49
	v_cvt_pk_bf16_f32 v49, v50, v51
	v_cvt_pk_bf16_f32 v50, v40, v41
	v_cvt_pk_bf16_f32 v51, v42, v43
	global_store_dwordx4 v[64:65], v[48:51], off offset:256
	v_cvt_pk_bf16_f32 v40, v52, v53
	v_cvt_pk_bf16_f32 v41, v54, v55
	v_cvt_pk_bf16_f32 v42, v44, v45
	v_add_co_u32_e32 v44, vcc, s70, v140
	s_nop 0
	v_lshl_add_u64 v[48:49], v[140:141], 0, s[18:19]
	v_addc_co_u32_e32 v45, vcc, 0, v141, vcc
	v_cvt_pk_bf16_f32 v43, v46, v47
	global_store_dwordx4 v[44:45], v[40:43], off
	v_cvt_pk_bf16_f32 v32, v32, v33
	v_cvt_pk_bf16_f32 v33, v34, v35
	v_cvt_pk_bf16_f32 v34, v24, v25
	v_cvt_pk_bf16_f32 v35, v26, v27
	global_store_dwordx4 v[48:49], v[32:35], off offset:256
	v_cvt_pk_bf16_f32 v24, v36, v37
	v_cvt_pk_bf16_f32 v25, v38, v39
	v_cvt_pk_bf16_f32 v26, v28, v29
	v_add_co_u32_e32 v28, vcc, s71, v140
	s_nop 0
	v_lshl_add_u64 v[32:33], v[140:141], 0, s[20:21]
	v_addc_co_u32_e32 v29, vcc, 0, v141, vcc
	v_cvt_pk_bf16_f32 v27, v30, v31
	global_store_dwordx4 v[28:29], v[24:27], off
	v_cvt_pk_bf16_f32 v16, v16, v17
	v_cvt_pk_bf16_f32 v17, v18, v19
	v_cvt_pk_bf16_f32 v18, v8, v9
	v_cvt_pk_bf16_f32 v19, v10, v11
	global_store_dwordx4 v[32:33], v[16:19], off offset:256
	v_cvt_pk_bf16_f32 v8, v20, v21
	v_cvt_pk_bf16_f32 v9, v22, v23
	v_cvt_pk_bf16_f32 v10, v12, v13
	v_add_co_u32_e32 v12, vcc, s73, v140
	s_nop 0
	v_lshl_add_u64 v[16:17], v[140:141], 0, s[30:31]
	v_addc_co_u32_e32 v13, vcc, 0, v141, vcc
	s_andn2_b64 vcc, exec, s[2:3]
	s_mov_b64 s[2:3], -1
	v_cvt_pk_bf16_f32 v11, v14, v15
	global_store_dwordx4 v[12:13], v[8:11], off
	v_cvt_pk_bf16_f32 v4, v4, v5
	v_cvt_pk_bf16_f32 v5, v6, v7
	v_cvt_pk_bf16_f32 v6, v0, v1
	v_cvt_pk_bf16_f32 v7, v2, v3
	global_store_dwordx4 v[16:17], v[4:7], off offset:256
	s_cbranch_vccnz .LBB0_417
	s_andn2_b64 vcc, exec, s[8:9]
	s_cbranch_vccnz .LBB0_416
	s_barrier
	s_branch .LBB0_416

.LBB0_680:
	s_lshl_b32 s0, s34, 8
	s_add_i32 s1, s0, 0xffffd000
	v_lshl_add_u32 v157, s48, 10, v150
	s_cmp_lt_i32 s34, 48
	ds_read_b32 v156, v157
	v_lshl_add_u32 v155, s30, 8, v148
	s_cselect_b32 s30, s0, s1
	s_cselect_b32 s0, s54, 0x48000000
	s_cselect_b32 s15, s53, 0x2000
	s_add_u32 s0, s4, s0
	v_or_b32_e32 v146, s30, v151
	s_addc_u32 s1, s5, 0
	v_ashrrev_i32_e32 v147, 31, v146
	v_lshl_add_u64 v[146:147], v[146:147], 1, s[0:1]
	v_mad_i64_i32 v[158:159], s[0:1], s15, v155, 0
	v_lshl_add_u64 v[158:159], v[158:159], 1, v[146:147]
	s_waitcnt lgkmcnt(0)
	v_pk_mul_f32 v[126:127], v[126:127], v[156:157] op_sel_hi:[1,0]
	v_pk_mul_f32 v[124:125], v[124:125], v[156:157] op_sel_hi:[1,0]
	v_pk_mul_f32 v[160:161], v[122:123], v[156:157] op_sel_hi:[1,0]
	v_pk_mul_f32 v[122:123], v[120:121], v[156:157] op_sel_hi:[1,0]
	v_cvt_pk_bf16_f32 v120, v124, v125
	v_cvt_pk_bf16_f32 v121, v126, v127
	v_pk_mul_f32 v[116:117], v[116:117], v[156:157] op_sel_hi:[1,0]
	v_cvt_pk_bf16_f32 v122, v122, v123
	v_cvt_pk_bf16_f32 v123, v160, v161
	global_store_dwordx4 v[158:159], v[120:123], off
	v_pk_mul_f32 v[118:119], v[118:119], v[156:157] op_sel_hi:[1,0]
	s_andn2_b64 vcc, exec, s[2:3]
	v_pk_mul_f32 v[120:121], v[114:115], v[156:157] op_sel_hi:[1,0]
	v_pk_mul_f32 v[114:115], v[112:113], v[156:157] op_sel_hi:[1,0]
	v_cvt_pk_bf16_f32 v112, v116, v117
	v_cvt_pk_bf16_f32 v113, v118, v119
	s_mov_b64 s[2:3], -1
	v_cvt_pk_bf16_f32 v114, v114, v115
	v_cvt_pk_bf16_f32 v115, v120, v121
	global_store_dwordx4 v[158:159], v[112:115], off offset:256
	ds_read_b32 v112, v157 offset:64
	s_nop 0
	v_or_b32_e32 v113, 16, v155
	v_mad_i64_i32 v[114:115], s[0:1], s15, v113, 0
	v_lshl_add_u64 v[114:115], v[114:115], 1, v[146:147]
	s_waitcnt lgkmcnt(0)
	v_pk_mul_f32 v[110:111], v[110:111], v[112:113] op_sel_hi:[1,0]
	v_pk_mul_f32 v[108:109], v[108:109], v[112:113] op_sel_hi:[1,0]
	v_pk_mul_f32 v[116:117], v[106:107], v[112:113] op_sel_hi:[1,0]
	v_pk_mul_f32 v[106:107], v[104:105], v[112:113] op_sel_hi:[1,0]
	v_cvt_pk_bf16_f32 v104, v108, v109
	v_cvt_pk_bf16_f32 v105, v110, v111
	v_pk_mul_f32 v[100:101], v[100:101], v[112:113] op_sel_hi:[1,0]
	v_cvt_pk_bf16_f32 v106, v106, v107
	v_cvt_pk_bf16_f32 v107, v116, v117
	global_store_dwordx4 v[114:115], v[104:107], off
	v_pk_mul_f32 v[102:103], v[102:103], v[112:113] op_sel_hi:[1,0]
	s_nop 0
	v_pk_mul_f32 v[104:105], v[98:99], v[112:113] op_sel_hi:[1,0]
	v_pk_mul_f32 v[98:99], v[96:97], v[112:113] op_sel_hi:[1,0]
	v_cvt_pk_bf16_f32 v96, v100, v101
	v_cvt_pk_bf16_f32 v97, v102, v103
	s_nop 0
	v_cvt_pk_bf16_f32 v98, v98, v99
	v_cvt_pk_bf16_f32 v99, v104, v105
	global_store_dwordx4 v[114:115], v[96:99], off offset:256
	ds_read_b32 v96, v157 offset:128
	s_nop 0
	v_or_b32_e32 v97, 32, v155
	v_mad_i64_i32 v[98:99], s[0:1], s15, v97, 0
	v_lshl_add_u64 v[98:99], v[98:99], 1, v[146:147]
	s_waitcnt lgkmcnt(0)
	v_pk_mul_f32 v[94:95], v[94:95], v[96:97] op_sel_hi:[1,0]
	v_pk_mul_f32 v[92:93], v[92:93], v[96:97] op_sel_hi:[1,0]
	v_pk_mul_f32 v[100:101], v[90:91], v[96:97] op_sel_hi:[1,0]
	v_pk_mul_f32 v[90:91], v[88:89], v[96:97] op_sel_hi:[1,0]
	v_cvt_pk_bf16_f32 v88, v92, v93
	v_cvt_pk_bf16_f32 v89, v94, v95
	v_pk_mul_f32 v[84:85], v[84:85], v[96:97] op_sel_hi:[1,0]
	v_cvt_pk_bf16_f32 v90, v90, v91
	v_cvt_pk_bf16_f32 v91, v100, v101
	global_store_dwordx4 v[98:99], v[88:91], off
	v_pk_mul_f32 v[86:87], v[86:87], v[96:97] op_sel_hi:[1,0]
	s_nop 0
	v_pk_mul_f32 v[88:89], v[82:83], v[96:97] op_sel_hi:[1,0]
	v_pk_mul_f32 v[82:83], v[80:81], v[96:97] op_sel_hi:[1,0]
	v_cvt_pk_bf16_f32 v80, v84, v85
	v_cvt_pk_bf16_f32 v81, v86, v87
	s_nop 0
	v_cvt_pk_bf16_f32 v82, v82, v83
	v_cvt_pk_bf16_f32 v83, v88, v89
	global_store_dwordx4 v[98:99], v[80:83], off offset:256
	ds_read_b32 v80, v157 offset:192
	s_nop 0
	v_or_b32_e32 v81, 48, v155
	v_mad_i64_i32 v[82:83], s[0:1], s15, v81, 0
	v_lshl_add_u64 v[82:83], v[82:83], 1, v[146:147]
	s_waitcnt lgkmcnt(0)
	v_pk_mul_f32 v[78:79], v[78:79], v[80:81] op_sel_hi:[1,0]
	v_pk_mul_f32 v[76:77], v[76:77], v[80:81] op_sel_hi:[1,0]
	v_pk_mul_f32 v[84:85], v[74:75], v[80:81] op_sel_hi:[1,0]
	v_pk_mul_f32 v[74:75], v[72:73], v[80:81] op_sel_hi:[1,0]
	v_cvt_pk_bf16_f32 v72, v76, v77
	v_cvt_pk_bf16_f32 v73, v78, v79
	v_pk_mul_f32 v[68:69], v[68:69], v[80:81] op_sel_hi:[1,0]
	v_cvt_pk_bf16_f32 v74, v74, v75
	v_cvt_pk_bf16_f32 v75, v84, v85
	global_store_dwordx4 v[82:83], v[72:75], off
	v_pk_mul_f32 v[70:71], v[70:71], v[80:81] op_sel_hi:[1,0]
	s_nop 0
	v_pk_mul_f32 v[72:73], v[66:67], v[80:81] op_sel_hi:[1,0]
	v_pk_mul_f32 v[66:67], v[64:65], v[80:81] op_sel_hi:[1,0]
	v_cvt_pk_bf16_f32 v64, v68, v69
	v_cvt_pk_bf16_f32 v65, v70, v71
	s_nop 0
	v_cvt_pk_bf16_f32 v66, v66, v67
	v_cvt_pk_bf16_f32 v67, v72, v73
	global_store_dwordx4 v[82:83], v[64:67], off offset:256
	ds_read_b32 v64, v157 offset:512
	s_nop 0
	v_add_u32_e32 v65, 0x80, v155
	v_mad_i64_i32 v[66:67], s[0:1], s15, v65, 0
	v_lshl_add_u64 v[66:67], v[66:67], 1, v[146:147]
	s_waitcnt lgkmcnt(0)
	v_pk_mul_f32 v[62:63], v[62:63], v[64:65] op_sel_hi:[1,0]
	v_pk_mul_f32 v[60:61], v[60:61], v[64:65] op_sel_hi:[1,0]
	v_pk_mul_f32 v[68:69], v[58:59], v[64:65] op_sel_hi:[1,0]
	v_pk_mul_f32 v[58:59], v[56:57], v[64:65] op_sel_hi:[1,0]
	v_cvt_pk_bf16_f32 v56, v60, v61
	v_cvt_pk_bf16_f32 v57, v62, v63
	v_pk_mul_f32 v[52:53], v[52:53], v[64:65] op_sel_hi:[1,0]
	v_cvt_pk_bf16_f32 v58, v58, v59
	v_cvt_pk_bf16_f32 v59, v68, v69
	global_store_dwordx4 v[66:67], v[56:59], off
	v_pk_mul_f32 v[54:55], v[54:55], v[64:65] op_sel_hi:[1,0]
	s_nop 0
	v_pk_mul_f32 v[56:57], v[50:51], v[64:65] op_sel_hi:[1,0]
	v_pk_mul_f32 v[50:51], v[48:49], v[64:65] op_sel_hi:[1,0]
	v_cvt_pk_bf16_f32 v48, v52, v53
	v_cvt_pk_bf16_f32 v49, v54, v55
	s_nop 0
	v_cvt_pk_bf16_f32 v50, v50, v51
	v_cvt_pk_bf16_f32 v51, v56, v57
	global_store_dwordx4 v[66:67], v[48:51], off offset:256
	ds_read_b32 v48, v157 offset:576
	s_nop 0
	v_add_u32_e32 v49, 0x90, v155
	v_mad_i64_i32 v[50:51], s[0:1], s15, v49, 0
	v_lshl_add_u64 v[50:51], v[50:51], 1, v[146:147]
	s_waitcnt lgkmcnt(0)
	v_pk_mul_f32 v[46:47], v[46:47], v[48:49] op_sel_hi:[1,0]
	v_pk_mul_f32 v[44:45], v[44:45], v[48:49] op_sel_hi:[1,0]
	v_pk_mul_f32 v[52:53], v[42:43], v[48:49] op_sel_hi:[1,0]
	v_pk_mul_f32 v[42:43], v[40:41], v[48:49] op_sel_hi:[1,0]
	v_cvt_pk_bf16_f32 v40, v44, v45
	v_cvt_pk_bf16_f32 v41, v46, v47
	v_pk_mul_f32 v[36:37], v[36:37], v[48:49] op_sel_hi:[1,0]
	v_cvt_pk_bf16_f32 v42, v42, v43
	v_cvt_pk_bf16_f32 v43, v52, v53
	global_store_dwordx4 v[50:51], v[40:43], off
	v_pk_mul_f32 v[38:39], v[38:39], v[48:49] op_sel_hi:[1,0]
	s_nop 0
	v_pk_mul_f32 v[40:41], v[34:35], v[48:49] op_sel_hi:[1,0]
	v_pk_mul_f32 v[34:35], v[32:33], v[48:49] op_sel_hi:[1,0]
	v_cvt_pk_bf16_f32 v32, v36, v37
	v_cvt_pk_bf16_f32 v33, v38, v39
	s_nop 0
	v_cvt_pk_bf16_f32 v34, v34, v35
	v_cvt_pk_bf16_f32 v35, v40, v41
	global_store_dwordx4 v[50:51], v[32:35], off offset:256
	ds_read_b32 v32, v157 offset:640
	s_nop 0
	v_add_u32_e32 v33, 0xa0, v155
	v_mad_i64_i32 v[34:35], s[0:1], s15, v33, 0
	v_lshl_add_u64 v[34:35], v[34:35], 1, v[146:147]
	s_waitcnt lgkmcnt(0)
	v_pk_mul_f32 v[30:31], v[30:31], v[32:33] op_sel_hi:[1,0]
	v_pk_mul_f32 v[28:29], v[28:29], v[32:33] op_sel_hi:[1,0]
	v_pk_mul_f32 v[36:37], v[26:27], v[32:33] op_sel_hi:[1,0]
	v_pk_mul_f32 v[26:27], v[24:25], v[32:33] op_sel_hi:[1,0]
	v_cvt_pk_bf16_f32 v24, v28, v29
	v_cvt_pk_bf16_f32 v25, v30, v31
	v_pk_mul_f32 v[20:21], v[20:21], v[32:33] op_sel_hi:[1,0]
	v_cvt_pk_bf16_f32 v26, v26, v27
	v_cvt_pk_bf16_f32 v27, v36, v37
	global_store_dwordx4 v[34:35], v[24:27], off
	v_pk_mul_f32 v[22:23], v[22:23], v[32:33] op_sel_hi:[1,0]
	s_nop 0
	v_pk_mul_f32 v[24:25], v[18:19], v[32:33] op_sel_hi:[1,0]
	v_pk_mul_f32 v[18:19], v[16:17], v[32:33] op_sel_hi:[1,0]
	v_cvt_pk_bf16_f32 v16, v20, v21
	v_cvt_pk_bf16_f32 v17, v22, v23
	s_nop 0
	v_cvt_pk_bf16_f32 v18, v18, v19
	v_cvt_pk_bf16_f32 v19, v24, v25
	global_store_dwordx4 v[34:35], v[16:19], off offset:256
	ds_read_b32 v16, v157 offset:704
	s_nop 0
	v_add_u32_e32 v17, 0xb0, v155
	v_mad_i64_i32 v[18:19], s[0:1], s15, v17, 0
	v_lshl_add_u64 v[18:19], v[18:19], 1, v[146:147]
	s_waitcnt lgkmcnt(0)
	v_pk_mul_f32 v[14:15], v[14:15], v[16:17] op_sel_hi:[1,0]
	v_pk_mul_f32 v[12:13], v[12:13], v[16:17] op_sel_hi:[1,0]
	v_pk_mul_f32 v[20:21], v[10:11], v[16:17] op_sel_hi:[1,0]
	v_pk_mul_f32 v[10:11], v[8:9], v[16:17] op_sel_hi:[1,0]
	v_cvt_pk_bf16_f32 v8, v12, v13
	v_cvt_pk_bf16_f32 v9, v14, v15
	v_pk_mul_f32 v[6:7], v[6:7], v[16:17] op_sel_hi:[1,0]
	v_cvt_pk_bf16_f32 v10, v10, v11
	v_cvt_pk_bf16_f32 v11, v20, v21
	global_store_dwordx4 v[18:19], v[8:11], off
	v_pk_mul_f32 v[4:5], v[4:5], v[16:17] op_sel_hi:[1,0]
	s_nop 0
	v_pk_mul_f32 v[8:9], v[2:3], v[16:17] op_sel_hi:[1,0]
	v_pk_mul_f32 v[2:3], v[0:1], v[16:17] op_sel_hi:[1,0]
	v_cvt_pk_bf16_f32 v0, v4, v5
	v_cvt_pk_bf16_f32 v1, v6, v7
	s_nop 0
	v_cvt_pk_bf16_f32 v2, v2, v3
	v_cvt_pk_bf16_f32 v3, v8, v9
	global_store_dwordx4 v[18:19], v[0:3], off offset:256
	s_cbranch_vccnz .LBB0_673
	s_andn2_b64 vcc, exec, s[6:7]
	s_xor_b32 s48, s48, 1
	s_cbranch_vccnz .LBB0_683
	s_lshl_b32 s0, s48, 10
	s_add_i32 s0, s0, 0
	s_add_i32 m0, s0, 0x20000
	s_lshl_b64 s[0:1], s[16:17], 10
	v_lshl_add_u64 v[0:1], v[136:137], 0, s[0:1]
	global_load_lds_dwordx4 v[0:1], off

.LBB0_1640:
	v_lshl_add_u32 v152, s40, 8, v146
	v_lshl_or_b32 v144, s63, 8, v148
	v_ashrrev_i32_e32 v153, 31, v152
	v_ashrrev_i32_e32 v145, 31, v144
	v_lshlrev_b64 v[154:155], 13, v[152:153]
	v_lshl_add_u64 v[154:155], s[12:13], 0, v[154:155]
	v_lshlrev_b64 v[156:157], 1, v[144:145]
	v_lshl_add_u64 v[144:145], v[154:155], 0, v[156:157]
	v_cvt_pk_bf16_f32 v124, v124, v125
	v_cvt_pk_bf16_f32 v125, v126, v127
	v_cvt_pk_bf16_f32 v126, v120, v121
	v_cvt_pk_bf16_f32 v127, v122, v123
	global_store_dwordx4 v[144:145], v[124:127], off
	v_cvt_pk_bf16_f32 v112, v112, v113
	v_cvt_pk_bf16_f32 v113, v114, v115
	v_cvt_pk_bf16_f32 v114, v104, v105
	v_or_b32_e32 v104, 16, v152
	v_ashrrev_i32_e32 v105, 31, v104
	v_lshlrev_b64 v[104:105], 13, v[104:105]
	v_lshl_add_u64 v[104:105], s[12:13], 0, v[104:105]
	v_cvt_pk_bf16_f32 v115, v106, v107
	global_store_dwordx4 v[144:145], v[112:115], off offset:256
	s_nop 1
	v_lshl_add_u64 v[112:113], v[104:105], 0, v[156:157]
	v_cvt_pk_bf16_f32 v104, v116, v117
	v_cvt_pk_bf16_f32 v105, v118, v119
	v_cvt_pk_bf16_f32 v106, v108, v109
	v_cvt_pk_bf16_f32 v107, v110, v111
	global_store_dwordx4 v[112:113], v[104:107], off
	v_cvt_pk_bf16_f32 v96, v96, v97
	v_cvt_pk_bf16_f32 v97, v98, v99
	v_cvt_pk_bf16_f32 v98, v88, v89
	v_or_b32_e32 v88, 32, v152
	v_ashrrev_i32_e32 v89, 31, v88
	v_lshlrev_b64 v[88:89], 13, v[88:89]
	v_lshl_add_u64 v[88:89], s[12:13], 0, v[88:89]
	v_cvt_pk_bf16_f32 v99, v90, v91
	global_store_dwordx4 v[112:113], v[96:99], off offset:256
	s_nop 1
	v_lshl_add_u64 v[96:97], v[88:89], 0, v[156:157]
	v_cvt_pk_bf16_f32 v88, v100, v101
	v_cvt_pk_bf16_f32 v89, v102, v103
	v_cvt_pk_bf16_f32 v90, v92, v93
	v_cvt_pk_bf16_f32 v91, v94, v95
	global_store_dwordx4 v[96:97], v[88:91], off
	v_cvt_pk_bf16_f32 v80, v80, v81
	v_cvt_pk_bf16_f32 v81, v82, v83
	v_cvt_pk_bf16_f32 v82, v72, v73
	v_or_b32_e32 v72, 48, v152
	v_ashrrev_i32_e32 v73, 31, v72
	v_lshlrev_b64 v[72:73], 13, v[72:73]
	v_lshl_add_u64 v[72:73], s[12:13], 0, v[72:73]
	v_cvt_pk_bf16_f32 v83, v74, v75
	global_store_dwordx4 v[96:97], v[80:83], off offset:256
	s_nop 1
	v_lshl_add_u64 v[80:81], v[72:73], 0, v[156:157]
	v_cvt_pk_bf16_f32 v72, v84, v85
	v_cvt_pk_bf16_f32 v73, v86, v87
	v_cvt_pk_bf16_f32 v74, v76, v77
	v_cvt_pk_bf16_f32 v75, v78, v79
	global_store_dwordx4 v[80:81], v[72:75], off
	v_cvt_pk_bf16_f32 v68, v68, v69
	v_cvt_pk_bf16_f32 v69, v70, v71
	v_cvt_pk_bf16_f32 v70, v64, v65
	v_cvt_pk_bf16_f32 v71, v66, v67
	global_store_dwordx4 v[80:81], v[68:71], off offset:256
	v_cvt_pk_bf16_f32 v60, v60, v61
	v_cvt_pk_bf16_f32 v61, v62, v63
	v_cvt_pk_bf16_f32 v62, v56, v57
	v_add_co_u32_e32 v56, vcc, s59, v144
	v_lshl_add_u64 v[64:65], v[144:145], 0, s[6:7]
	s_nop 0
	v_addc_co_u32_e32 v57, vcc, 0, v145, vcc
	v_cvt_pk_bf16_f32 v63, v58, v59
	global_store_dwordx4 v[56:57], v[60:63], off
	v_cvt_pk_bf16_f32 v48, v48, v49
	v_cvt_pk_bf16_f32 v49, v50, v51
	v_cvt_pk_bf16_f32 v50, v40, v41
	v_cvt_pk_bf16_f32 v51, v42, v43
	global_store_dwordx4 v[64:65], v[48:51], off offset:256
	v_cvt_pk_bf16_f32 v40, v52, v53
	v_cvt_pk_bf16_f32 v41, v54, v55
	v_cvt_pk_bf16_f32 v42, v44, v45
	v_add_co_u32_e32 v44, vcc, s60, v144
	s_nop 0
	v_lshl_add_u64 v[48:49], v[144:145], 0, s[18:19]
	v_addc_co_u32_e32 v45, vcc, 0, v145, vcc
	v_cvt_pk_bf16_f32 v43, v46, v47
	global_store_dwordx4 v[44:45], v[40:43], off
	v_cvt_pk_bf16_f32 v32, v32, v33
	v_cvt_pk_bf16_f32 v33, v34, v35
	v_cvt_pk_bf16_f32 v34, v24, v25
	v_cvt_pk_bf16_f32 v35, v26, v27
	global_store_dwordx4 v[48:49], v[32:35], off offset:256
	v_cvt_pk_bf16_f32 v24, v36, v37
	v_cvt_pk_bf16_f32 v25, v38, v39
	v_cvt_pk_bf16_f32 v26, v28, v29
	v_add_co_u32_e32 v28, vcc, s61, v144
	s_nop 0
	v_lshl_add_u64 v[32:33], v[144:145], 0, s[20:21]
	v_addc_co_u32_e32 v29, vcc, 0, v145, vcc
	v_cvt_pk_bf16_f32 v27, v30, v31
	global_store_dwordx4 v[28:29], v[24:27], off
	v_cvt_pk_bf16_f32 v16, v16, v17
	v_cvt_pk_bf16_f32 v17, v18, v19
	v_cvt_pk_bf16_f32 v18, v8, v9
	v_cvt_pk_bf16_f32 v19, v10, v11
	global_store_dwordx4 v[32:33], v[16:19], off offset:256
	v_cvt_pk_bf16_f32 v8, v20, v21
	v_cvt_pk_bf16_f32 v9, v22, v23
	v_cvt_pk_bf16_f32 v10, v12, v13
	v_add_co_u32_e32 v12, vcc, s62, v144
	s_nop 0
	v_lshl_add_u64 v[16:17], v[144:145], 0, s[28:29]
	v_addc_co_u32_e32 v13, vcc, 0, v145, vcc
	s_andn2_b64 vcc, exec, s[4:5]
	s_mov_b64 s[4:5], -1
	v_cvt_pk_bf16_f32 v11, v14, v15
	global_store_dwordx4 v[12:13], v[8:11], off
	v_cvt_pk_bf16_f32 v4, v4, v5
	v_cvt_pk_bf16_f32 v5, v6, v7
	v_cvt_pk_bf16_f32 v6, v0, v1
	v_cvt_pk_bf16_f32 v7, v2, v3
	global_store_dwordx4 v[16:17], v[4:7], off offset:256
	s_cbranch_vccnz .LBB0_1629
	s_andn2_b64 vcc, exec, s[10:11]
	s_cbranch_vccnz .LBB0_1628
	s_barrier
	s_branch .LBB0_1628

.LBB0_1983:
	v_lshl_add_u32 v6, s42, 8, v181
	v_lshl_or_b32 v0, s73, 8, v183
	v_ashrrev_i32_e32 v7, 31, v6
	v_ashrrev_i32_e32 v1, 31, v0
	v_lshlrev_b64 v[2:3], 13, v[6:7]
	v_lshl_add_u64 v[2:3], s[10:11], 0, v[2:3]
	v_lshlrev_b64 v[8:9], 1, v[0:1]
	s_nop 15
	s_nop 15
	v_lshl_add_u64 v[0:1], v[2:3], 0, v[8:9]
	v_pk_mul_f32 v[2:3], v[156:157], s[16:17] op_sel_hi:[1,0]
	v_pk_mul_f32 v[4:5], v[158:159], s[16:17] op_sel_hi:[1,0]
	v_cvt_pk_bf16_f32 v2, v2, v3
	v_pk_mul_f32 v[10:11], v[154:155], s[16:17] op_sel_hi:[1,0]
	v_cvt_pk_bf16_f32 v3, v4, v5
	v_pk_mul_f32 v[12:13], v[152:153], s[16:17] op_sel_hi:[1,0]
	v_pk_mul_f32 v[14:15], v[136:137], s[16:17] op_sel_hi:[1,0]
	v_cvt_pk_bf16_f32 v4, v12, v13
	v_cvt_pk_bf16_f32 v5, v10, v11
	global_store_dwordx4 v[0:1], v[2:5], off
	v_pk_mul_f32 v[10:11], v[142:143], s[16:17] op_sel_hi:[1,0]
	v_pk_mul_f32 v[12:13], v[140:141], s[16:17] op_sel_hi:[1,0]
	v_pk_mul_f32 v[2:3], v[148:149], s[16:17] op_sel_hi:[1,0]
	v_pk_mul_f32 v[4:5], v[150:151], s[16:17] op_sel_hi:[1,0]
	v_cvt_pk_bf16_f32 v2, v2, v3
	s_nop 0
	v_cvt_pk_bf16_f32 v3, v4, v5
	v_cvt_pk_bf16_f32 v4, v12, v13
	v_cvt_pk_bf16_f32 v5, v10, v11
	global_store_dwordx4 v[0:1], v[2:5], off offset:256
	v_pk_mul_f32 v[12:13], v[138:139], s[16:17] op_sel_hi:[1,0]
	s_nop 0
	v_or_b32_e32 v2, 16, v6
	v_ashrrev_i32_e32 v3, 31, v2
	v_lshlrev_b64 v[2:3], 13, v[2:3]
	v_lshl_add_u64 v[2:3], s[10:11], 0, v[2:3]
	v_lshl_add_u64 v[10:11], v[2:3], 0, v[8:9]
	v_pk_mul_f32 v[2:3], v[144:145], s[16:17] op_sel_hi:[1,0]
	v_pk_mul_f32 v[4:5], v[146:147], s[16:17] op_sel_hi:[1,0]
	v_cvt_pk_bf16_f32 v2, v2, v3
	s_nop 0
	v_cvt_pk_bf16_f32 v3, v4, v5
	v_cvt_pk_bf16_f32 v4, v14, v15
	v_cvt_pk_bf16_f32 v5, v12, v13
	global_store_dwordx4 v[10:11], v[2:5], off
	v_pk_mul_f32 v[12:13], v[126:127], s[16:17] op_sel_hi:[1,0]
	v_pk_mul_f32 v[14:15], v[124:125], s[16:17] op_sel_hi:[1,0]
	v_pk_mul_f32 v[2:3], v[132:133], s[16:17] op_sel_hi:[1,0]
	v_pk_mul_f32 v[4:5], v[134:135], s[16:17] op_sel_hi:[1,0]
	v_cvt_pk_bf16_f32 v2, v2, v3
	s_nop 0
	v_cvt_pk_bf16_f32 v3, v4, v5
	v_cvt_pk_bf16_f32 v4, v14, v15
	v_cvt_pk_bf16_f32 v5, v12, v13
	global_store_dwordx4 v[10:11], v[2:5], off offset:256
	v_pk_mul_f32 v[12:13], v[122:123], s[16:17] op_sel_hi:[1,0]
	v_pk_mul_f32 v[14:15], v[120:121], s[16:17] op_sel_hi:[1,0]
	v_or_b32_e32 v2, 32, v6
	v_ashrrev_i32_e32 v3, 31, v2
	v_lshlrev_b64 v[2:3], 13, v[2:3]
	v_lshl_add_u64 v[2:3], s[10:11], 0, v[2:3]
	v_lshl_add_u64 v[10:11], v[2:3], 0, v[8:9]
	v_pk_mul_f32 v[2:3], v[128:129], s[16:17] op_sel_hi:[1,0]
	v_pk_mul_f32 v[4:5], v[130:131], s[16:17] op_sel_hi:[1,0]
	v_cvt_pk_bf16_f32 v2, v2, v3
	s_nop 0
	v_cvt_pk_bf16_f32 v3, v4, v5
	v_cvt_pk_bf16_f32 v4, v14, v15
	v_cvt_pk_bf16_f32 v5, v12, v13
	global_store_dwordx4 v[10:11], v[2:5], off
	v_pk_mul_f32 v[12:13], v[110:111], s[16:17] op_sel_hi:[1,0]
	v_pk_mul_f32 v[14:15], v[108:109], s[16:17] op_sel_hi:[1,0]
	v_pk_mul_f32 v[2:3], v[116:117], s[16:17] op_sel_hi:[1,0]
	v_pk_mul_f32 v[4:5], v[118:119], s[16:17] op_sel_hi:[1,0]
	v_cvt_pk_bf16_f32 v2, v2, v3
	s_nop 0
	v_cvt_pk_bf16_f32 v3, v4, v5
	v_cvt_pk_bf16_f32 v4, v14, v15
	v_cvt_pk_bf16_f32 v5, v12, v13
	global_store_dwordx4 v[10:11], v[2:5], off offset:256
	v_pk_mul_f32 v[10:11], v[104:105], s[16:17] op_sel_hi:[1,0]
	s_nop 0
	v_or_b32_e32 v2, 48, v6
	v_ashrrev_i32_e32 v3, 31, v2
	v_lshlrev_b64 v[2:3], 13, v[2:3]
	v_lshl_add_u64 v[2:3], s[10:11], 0, v[2:3]
	v_lshl_add_u64 v[6:7], v[2:3], 0, v[8:9]
	v_pk_mul_f32 v[4:5], v[114:115], s[16:17] op_sel_hi:[1,0]
	v_pk_mul_f32 v[2:3], v[112:113], s[16:17] op_sel_hi:[1,0]
	v_pk_mul_f32 v[8:9], v[106:107], s[16:17] op_sel_hi:[1,0]
	v_cvt_pk_bf16_f32 v2, v2, v3
	v_cvt_pk_bf16_f32 v3, v4, v5
	v_cvt_pk_bf16_f32 v4, v10, v11
	v_pk_mul_f32 v[10:11], v[96:97], s[16:17] op_sel_hi:[1,0]
	v_cvt_pk_bf16_f32 v5, v8, v9
	global_store_dwordx4 v[6:7], v[2:5], off
	v_pk_mul_f32 v[8:9], v[98:99], s[16:17] op_sel_hi:[1,0]
	s_nop 0
	v_pk_mul_f32 v[4:5], v[102:103], s[16:17] op_sel_hi:[1,0]
	v_pk_mul_f32 v[2:3], v[100:101], s[16:17] op_sel_hi:[1,0]
	s_nop 0
	v_cvt_pk_bf16_f32 v2, v2, v3
	v_cvt_pk_bf16_f32 v3, v4, v5
	v_cvt_pk_bf16_f32 v4, v10, v11
	v_cvt_pk_bf16_f32 v5, v8, v9
	global_store_dwordx4 v[6:7], v[2:5], off offset:256
	v_pk_mul_f32 v[8:9], v[90:91], s[16:17] op_sel_hi:[1,0]
	v_pk_mul_f32 v[10:11], v[88:89], s[16:17] op_sel_hi:[1,0]
	v_pk_mul_f32 v[4:5], v[94:95], s[16:17] op_sel_hi:[1,0]
	v_pk_mul_f32 v[2:3], v[92:93], s[16:17] op_sel_hi:[1,0]
	v_lshl_add_u64 v[6:7], v[0:1], 0, s[18:19]
	v_cvt_pk_bf16_f32 v2, v2, v3
	v_cvt_pk_bf16_f32 v3, v4, v5
	v_cvt_pk_bf16_f32 v4, v10, v11
	v_cvt_pk_bf16_f32 v5, v8, v9
	v_add_co_u32_e32 v8, vcc, s67, v0
	v_pk_mul_f32 v[10:11], v[76:77], s[16:17] op_sel_hi:[1,0]
	s_nop 0
	v_addc_co_u32_e32 v9, vcc, 0, v1, vcc
	global_store_dwordx4 v[8:9], v[2:5], off
	v_pk_mul_f32 v[8:9], v[78:79], s[16:17] op_sel_hi:[1,0]
	s_nop 0
	v_pk_mul_f32 v[4:5], v[86:87], s[16:17] op_sel_hi:[1,0]
	v_pk_mul_f32 v[2:3], v[84:85], s[16:17] op_sel_hi:[1,0]
	s_nop 0
	v_cvt_pk_bf16_f32 v2, v2, v3
	v_cvt_pk_bf16_f32 v3, v4, v5
	v_cvt_pk_bf16_f32 v4, v10, v11
	v_cvt_pk_bf16_f32 v5, v8, v9
	global_store_dwordx4 v[6:7], v[2:5], off offset:256
	v_pk_mul_f32 v[8:9], v[74:75], s[16:17] op_sel_hi:[1,0]
	v_pk_mul_f32 v[10:11], v[72:73], s[16:17] op_sel_hi:[1,0]
	v_pk_mul_f32 v[4:5], v[82:83], s[16:17] op_sel_hi:[1,0]
	v_pk_mul_f32 v[2:3], v[80:81], s[16:17] op_sel_hi:[1,0]
	v_lshl_add_u64 v[6:7], v[0:1], 0, s[20:21]
	v_cvt_pk_bf16_f32 v2, v2, v3
	v_cvt_pk_bf16_f32 v3, v4, v5
	v_cvt_pk_bf16_f32 v4, v10, v11
	v_cvt_pk_bf16_f32 v5, v8, v9
	v_add_co_u32_e32 v8, vcc, s68, v0
	v_pk_mul_f32 v[10:11], v[60:61], s[16:17] op_sel_hi:[1,0]
	s_nop 0
	v_addc_co_u32_e32 v9, vcc, 0, v1, vcc
	global_store_dwordx4 v[8:9], v[2:5], off
	v_pk_mul_f32 v[8:9], v[62:63], s[16:17] op_sel_hi:[1,0]
	s_nop 0
	v_pk_mul_f32 v[4:5], v[70:71], s[16:17] op_sel_hi:[1,0]
	v_pk_mul_f32 v[2:3], v[68:69], s[16:17] op_sel_hi:[1,0]
	s_nop 0
	v_cvt_pk_bf16_f32 v2, v2, v3
	v_cvt_pk_bf16_f32 v3, v4, v5
	v_cvt_pk_bf16_f32 v4, v10, v11
	v_cvt_pk_bf16_f32 v5, v8, v9
	global_store_dwordx4 v[6:7], v[2:5], off offset:256
	v_pk_mul_f32 v[8:9], v[58:59], s[16:17] op_sel_hi:[1,0]
	v_pk_mul_f32 v[10:11], v[56:57], s[16:17] op_sel_hi:[1,0]
	v_pk_mul_f32 v[4:5], v[66:67], s[16:17] op_sel_hi:[1,0]
	v_pk_mul_f32 v[2:3], v[64:65], s[16:17] op_sel_hi:[1,0]
	v_lshl_add_u64 v[6:7], v[0:1], 0, s[28:29]
	v_cvt_pk_bf16_f32 v2, v2, v3
	v_cvt_pk_bf16_f32 v3, v4, v5
	v_cvt_pk_bf16_f32 v4, v10, v11
	v_cvt_pk_bf16_f32 v5, v8, v9
	v_add_co_u32_e32 v8, vcc, s69, v0
	v_pk_mul_f32 v[10:11], v[44:45], s[16:17] op_sel_hi:[1,0]
	s_nop 0
	v_addc_co_u32_e32 v9, vcc, 0, v1, vcc
	global_store_dwordx4 v[8:9], v[2:5], off
	v_pk_mul_f32 v[8:9], v[46:47], s[16:17] op_sel_hi:[1,0]
	s_nop 0
	v_pk_mul_f32 v[2:3], v[52:53], s[16:17] op_sel_hi:[1,0]
	v_pk_mul_f32 v[4:5], v[54:55], s[16:17] op_sel_hi:[1,0]
	v_cvt_pk_bf16_f32 v2, v2, v3
	s_nop 0
	v_cvt_pk_bf16_f32 v3, v4, v5
	v_cvt_pk_bf16_f32 v4, v10, v11
	v_cvt_pk_bf16_f32 v5, v8, v9
	global_store_dwordx4 v[6:7], v[2:5], off offset:256
	v_lshl_add_u64 v[6:7], v[0:1], 0, s[30:31]
	v_add_co_u32_e32 v0, vcc, s70, v0
	v_pk_mul_f32 v[2:3], v[48:49], s[16:17] op_sel_hi:[1,0]
	v_pk_mul_f32 v[4:5], v[50:51], s[16:17] op_sel_hi:[1,0]
	v_cvt_pk_bf16_f32 v2, v2, v3
	v_addc_co_u32_e32 v1, vcc, 0, v1, vcc
	v_cvt_pk_bf16_f32 v3, v4, v5
	v_pk_mul_f32 v[8:9], v[42:43], s[16:17] op_sel_hi:[1,0]
	v_pk_mul_f32 v[10:11], v[40:41], s[16:17] op_sel_hi:[1,0]
	s_andn2_b64 vcc, exec, s[2:3]
	v_cvt_pk_bf16_f32 v4, v10, v11
	v_cvt_pk_bf16_f32 v5, v8, v9
	global_store_dwordx4 v[0:1], v[2:5], off
	v_pk_mul_f32 v[0:1], v[36:37], s[16:17] op_sel_hi:[1,0]
	s_mov_b64 s[2:3], -1
	v_pk_mul_f32 v[2:3], v[38:39], s[16:17] op_sel_hi:[1,0]
	v_pk_mul_f32 v[4:5], v[34:35], s[16:17] op_sel_hi:[1,0]
	v_pk_mul_f32 v[8:9], v[32:33], s[16:17] op_sel_hi:[1,0]
	v_cvt_pk_bf16_f32 v0, v0, v1
	v_cvt_pk_bf16_f32 v1, v2, v3
	s_nop 0
	v_cvt_pk_bf16_f32 v2, v8, v9
	v_cvt_pk_bf16_f32 v3, v4, v5
	global_store_dwordx4 v[6:7], v[0:3], off offset:256
	s_cbranch_vccnz .LBB0_1966
	s_andn2_b64 vcc, exec, s[8:9]
	s_cbranch_vccnz .LBB0_1965
	s_barrier
	s_branch .LBB0_1965
